# phase-0 RMSNorm: a wave's 8 rows loaded together (32 loads in flight), reductions interleaved, gain vector loaded once; same arithmetic order
# speedup vs baseline: 1.0109x; 1.0021x over previous
; __device__ __forceinline__ float bflo(unsigned w) { return __uint_as_float(w << 16); }
; __device__ __forceinline__ float bfhi(unsigned w) { return __uint_as_float(w & 0xffff0000u); }
; __device__ __forceinline__ int opaque_bid() { int t = blockIdx.x; asm volatile("" : "+s"(t)); return t; }
; __device__ __forceinline__ int opaque_gd() { int t = gridDim.x; asm volatile("" : "+s"(t)); return t; }
; __device__ __forceinline__ int opaque_tid() { int t = threadIdx.x; asm volatile("" : "+v"(t)); return t; }
; __device__ __forceinline__ void norm_phase(const float* y, const float* gy, const float* xin, float* xo, const float* gn, bf16_t* h) {
;     const int tid = opaque_tid(), wid = tid >> 6, lane = tid & 63;
;     for (int row = opaque_bid() * 8 + wid; row < M; row += opaque_gd() * 8) {
;         f32x4 xv[4]; const float* xr = xin + (size_t)row * D + lane * 4;
; #pragma unroll
;         for (int i = 0; i < 4; ++i) xv[i] = *(const f32x4*)(xr + i * 256);
;         if (y) {
;             f32x4 yv[4]; const bf16_t* yr = (const bf16_t*)y + (size_t)row * D + lane * 4; float ss = 0.f;
; #pragma unroll
;             for (int i = 0; i < 4; ++i) { const u32x2 yw = *(const u32x2*)(yr + i * 256); yv[i] = (f32x4){bflo(yw.x), bfhi(yw.x), bflo(yw.y), bfhi(yw.y)}; ss += yv[i][0] * yv[i][0] + yv[i][1] * yv[i][1] + yv[i][2] * yv[i][2] + yv[i][3] * yv[i][3]; }
;             ss = wave_sum(ss); const float rs = rsqrtf(ss * (1.f / 1024.f) + EPS);
; #pragma unroll
;             for (int i = 0; i < 4; ++i) { const f32x4 gv = *(const f32x4*)(gy + lane * 4 + i * 256); xv[i] += yv[i] * rs * gv; }
;         }
;         if (xo) {
; #pragma unroll
;             for (int i = 0; i < 4; ++i) *(f32x4*)(xo + (size_t)row * D + lane * 4 + i * 256) = xv[i];
;         }
;         if (h) {
;             float ss = 0.f;
; #pragma unroll
;             for (int i = 0; i < 4; ++i) ss += xv[i][0] * xv[i][0] + xv[i][1] * xv[i][1] + xv[i][2] * xv[i][2] + xv[i][3] * xv[i][3];
;             ss = wave_sum(ss); const float rs = rsqrtf(ss * (1.f / 1024.f) + EPS);
.LBB0_732:
	s_or_b64 exec, exec, s[22:23]
	v_mov_b32_e32 v1, v202
	s_mov_b32 s0, s91
	s_nop 0
	v_ashrrev_i32_e32 v0, 6, v1
	v_lshl_add_u32 v0, s0, 3, v0
	s_movk_i32 s0, 0x4000
	v_cmp_gt_i32_e32 vcc, s0, v0
	s_and_saveexec_b64 s[4:5], vcc
	s_cbranch_execz .LBB0_8
	s_cmp_lg_u32 s90, 0x100
	s_cbranch_scc1 .Lnorm0_slow
	s_cmp_eq_u64 s[18:19], 0
	s_cbranch_scc1 .Lnorm0_slow
	v_readlane_b32 s0, v255, 16
	v_readlane_b32 s1, v255, 17
	v_readlane_b32 s6, v255, 18
	v_readlane_b32 s7, v255, 19
	v_readfirstlane_b32 s8, v0
	v_lshlrev_b32_e32 v3, 4, v207
	v_lshlrev_b32_e32 v4, 3, v207
	v_xor_b32_e32 v44, 32, v207
	v_xor_b32_e32 v45, 16, v207
	v_xor_b32_e32 v46, 8, v207
	v_xor_b32_e32 v47, 4, v207
	v_xor_b32_e32 v5, 2, v207
	v_xor_b32_e32 v6, 1, v207
	v_lshlrev_b32_e32 v44, 2, v44
	v_lshlrev_b32_e32 v45, 2, v45
	v_lshlrev_b32_e32 v46, 2, v46
	v_lshlrev_b32_e32 v47, 2, v47
	v_lshlrev_b32_e32 v5, 2, v5
	v_lshlrev_b32_e32 v6, 2, v6
	s_lshl_b32 s9, s8, 12
	s_add_u32 s0, s0, s9
	s_addc_u32 s1, s1, 0
	s_lshl_b32 s9, s8, 11
	s_add_u32 s10, s18, s9
	s_addc_u32 s11, s19, 0
	global_load_dwordx4 v[12:15], v3, s[6:7] offset:0
	global_load_dwordx4 v[16:19], v3, s[6:7] offset:1024
	global_load_dwordx4 v[20:23], v3, s[6:7] offset:2048
	global_load_dwordx4 v[24:27], v3, s[6:7] offset:3072
	global_load_dwordx4 v[48:51], v3, s[0:1] offset:0
	global_load_dwordx4 v[52:55], v3, s[0:1] offset:1024
	global_load_dwordx4 v[56:59], v3, s[0:1] offset:2048
	global_load_dwordx4 v[60:63], v3, s[0:1] offset:3072
	s_add_u32 s0, s0, 0x800000
	s_addc_u32 s1, s1, 0
	global_load_dwordx4 v[64:67], v3, s[0:1] offset:0
	global_load_dwordx4 v[68:71], v3, s[0:1] offset:1024
	global_load_dwordx4 v[72:75], v3, s[0:1] offset:2048
	global_load_dwordx4 v[76:79], v3, s[0:1] offset:3072
	s_add_u32 s0, s0, 0x800000
	s_addc_u32 s1, s1, 0
	global_load_dwordx4 v[80:83], v3, s[0:1] offset:0
	global_load_dwordx4 v[84:87], v3, s[0:1] offset:1024
	global_load_dwordx4 v[88:91], v3, s[0:1] offset:2048
	global_load_dwordx4 v[92:95], v3, s[0:1] offset:3072
	s_add_u32 s0, s0, 0x800000
	s_addc_u32 s1, s1, 0
	global_load_dwordx4 v[96:99], v3, s[0:1] offset:0
	global_load_dwordx4 v[100:103], v3, s[0:1] offset:1024
	global_load_dwordx4 v[104:107], v3, s[0:1] offset:2048
	global_load_dwordx4 v[108:111], v3, s[0:1] offset:3072
	s_add_u32 s0, s0, 0x800000
	s_addc_u32 s1, s1, 0
	global_load_dwordx4 v[112:115], v3, s[0:1] offset:0
	global_load_dwordx4 v[116:119], v3, s[0:1] offset:1024
	global_load_dwordx4 v[120:123], v3, s[0:1] offset:2048
	global_load_dwordx4 v[124:127], v3, s[0:1] offset:3072
	s_add_u32 s0, s0, 0x800000
	s_addc_u32 s1, s1, 0
	global_load_dwordx4 v[128:131], v3, s[0:1] offset:0
	global_load_dwordx4 v[132:135], v3, s[0:1] offset:1024
	global_load_dwordx4 v[148:151], v3, s[0:1] offset:2048
	global_load_dwordx4 v[152:155], v3, s[0:1] offset:3072
	s_add_u32 s0, s0, 0x800000
	s_addc_u32 s1, s1, 0
	global_load_dwordx4 v[156:159], v3, s[0:1] offset:0
	global_load_dwordx4 v[160:163], v3, s[0:1] offset:1024
	global_load_dwordx4 v[164:167], v3, s[0:1] offset:2048
	global_load_dwordx4 v[168:171], v3, s[0:1] offset:3072
	s_add_u32 s0, s0, 0x800000
	s_addc_u32 s1, s1, 0
	global_load_dwordx4 v[172:175], v3, s[0:1] offset:0
	global_load_dwordx4 v[176:179], v3, s[0:1] offset:1024
	global_load_dwordx4 v[180:183], v3, s[0:1] offset:2048
	global_load_dwordx4 v[184:187], v3, s[0:1] offset:3072
	s_waitcnt vmcnt(28)
	v_mul_f32_e32 v36, v53, v53
	v_mul_f32_e32 v28, v49, v49
	v_mul_f32_e32 v7, v61, v61
	v_mul_f32_e32 v8, v57, v57
	v_fma_f32 v36, v52, v52, v36
	v_fma_f32 v28, v48, v48, v28
	v_fma_f32 v7, v60, v60, v7
	v_fma_f32 v8, v56, v56, v8
	v_fma_f32 v36, v54, v54, v36
	v_fma_f32 v28, v50, v50, v28
	v_fma_f32 v7, v62, v62, v7
	v_fma_f32 v8, v58, v58, v8
	v_fma_f32 v36, v55, v55, v36
	v_fma_f32 v28, v51, v51, v28
	v_fma_f32 v7, v63, v63, v7
	v_fma_f32 v8, v59, v59, v8
	v_add_f32_e32 v28, v36, v28
	v_add_f32_e32 v28, v8, v28
	v_add_f32_e32 v28, v7, v28
	s_waitcnt vmcnt(24)
	v_mul_f32_e32 v37, v69, v69
	v_mul_f32_e32 v29, v65, v65
	v_mul_f32_e32 v7, v77, v77
	v_mul_f32_e32 v8, v73, v73
	v_fma_f32 v37, v68, v68, v37
	v_fma_f32 v29, v64, v64, v29
	v_fma_f32 v7, v76, v76, v7
	v_fma_f32 v8, v72, v72, v8
	v_fma_f32 v37, v70, v70, v37
	v_fma_f32 v29, v66, v66, v29
	v_fma_f32 v7, v78, v78, v7
	v_fma_f32 v8, v74, v74, v8
	v_fma_f32 v37, v71, v71, v37
	v_fma_f32 v29, v67, v67, v29
	v_fma_f32 v7, v79, v79, v7
	v_fma_f32 v8, v75, v75, v8
	v_add_f32_e32 v29, v37, v29
	v_add_f32_e32 v29, v8, v29
	v_add_f32_e32 v29, v7, v29
	s_waitcnt vmcnt(20)
	v_mul_f32_e32 v38, v85, v85
	v_mul_f32_e32 v30, v81, v81
	v_mul_f32_e32 v7, v93, v93
	v_mul_f32_e32 v8, v89, v89
	v_fma_f32 v38, v84, v84, v38
	v_fma_f32 v30, v80, v80, v30
	v_fma_f32 v7, v92, v92, v7
	v_fma_f32 v8, v88, v88, v8
	v_fma_f32 v38, v86, v86, v38
	v_fma_f32 v30, v82, v82, v30
	v_fma_f32 v7, v94, v94, v7
	v_fma_f32 v8, v90, v90, v8
	v_fma_f32 v38, v87, v87, v38
	v_fma_f32 v30, v83, v83, v30
	v_fma_f32 v7, v95, v95, v7
	v_fma_f32 v8, v91, v91, v8
	v_add_f32_e32 v30, v38, v30
	v_add_f32_e32 v30, v8, v30
	v_add_f32_e32 v30, v7, v30
	s_waitcnt vmcnt(16)
	v_mul_f32_e32 v39, v101, v101
	v_mul_f32_e32 v31, v97, v97
	v_mul_f32_e32 v7, v109, v109
	v_mul_f32_e32 v8, v105, v105
	v_fma_f32 v39, v100, v100, v39
	v_fma_f32 v31, v96, v96, v31
	v_fma_f32 v7, v108, v108, v7
	v_fma_f32 v8, v104, v104, v8
	v_fma_f32 v39, v102, v102, v39
	v_fma_f32 v31, v98, v98, v31
	v_fma_f32 v7, v110, v110, v7
	v_fma_f32 v8, v106, v106, v8
	v_fma_f32 v39, v103, v103, v39
	v_fma_f32 v31, v99, v99, v31
	v_fma_f32 v7, v111, v111, v7
	v_fma_f32 v8, v107, v107, v8
	v_add_f32_e32 v31, v39, v31
	v_add_f32_e32 v31, v8, v31
	v_add_f32_e32 v31, v7, v31
	s_waitcnt vmcnt(12)
; __device__ __forceinline__ float wave_sum(float v) {
; #pragma unroll
;     for (int o = 32; o >= 1; o >>= 1) v += __shfl_xor(v, o);
;     return v;
; __device__ __forceinline__ void norm_phase(const float* y, const float* gy, const float* xin, float* xo, const float* gn, bf16_t* h) {
;     ...
;             for (int i = 0; i < 4; ++i) ss += xv[i][0] * xv[i][0] + xv[i][1] * xv[i][1] + xv[i][2] * xv[i][2] + xv[i][3] * xv[i][3];
;             ss = wave_sum(ss); const float rs = rsqrtf(ss * (1.f / 1024.f) + EPS);
	v_mul_f32_e32 v40, v117, v117
	v_mul_f32_e32 v32, v113, v113
	v_mul_f32_e32 v7, v125, v125
	v_mul_f32_e32 v8, v121, v121
	v_fma_f32 v40, v116, v116, v40
	v_fma_f32 v32, v112, v112, v32
	v_fma_f32 v7, v124, v124, v7
	v_fma_f32 v8, v120, v120, v8
	v_fma_f32 v40, v118, v118, v40
	v_fma_f32 v32, v114, v114, v32
	v_fma_f32 v7, v126, v126, v7
	v_fma_f32 v8, v122, v122, v8
	v_fma_f32 v40, v119, v119, v40
	v_fma_f32 v32, v115, v115, v32
	v_fma_f32 v7, v127, v127, v7
	v_fma_f32 v8, v123, v123, v8
	v_add_f32_e32 v32, v40, v32
	v_add_f32_e32 v32, v8, v32
	v_add_f32_e32 v32, v7, v32
	s_waitcnt vmcnt(8)
	v_mul_f32_e32 v41, v133, v133
	v_mul_f32_e32 v33, v129, v129
	v_mul_f32_e32 v7, v153, v153
	v_mul_f32_e32 v8, v149, v149
	v_fma_f32 v41, v132, v132, v41
	v_fma_f32 v33, v128, v128, v33
	v_fma_f32 v7, v152, v152, v7
	v_fma_f32 v8, v148, v148, v8
	v_fma_f32 v41, v134, v134, v41
	v_fma_f32 v33, v130, v130, v33
	v_fma_f32 v7, v154, v154, v7
	v_fma_f32 v8, v150, v150, v8
	v_fma_f32 v41, v135, v135, v41
	v_fma_f32 v33, v131, v131, v33
	v_fma_f32 v7, v155, v155, v7
	v_fma_f32 v8, v151, v151, v8
	v_add_f32_e32 v33, v41, v33
	v_add_f32_e32 v33, v8, v33
	v_add_f32_e32 v33, v7, v33
	s_waitcnt vmcnt(4)
	v_mul_f32_e32 v42, v161, v161
	v_mul_f32_e32 v34, v157, v157
	v_mul_f32_e32 v7, v169, v169
	v_mul_f32_e32 v8, v165, v165
	v_fma_f32 v42, v160, v160, v42
	v_fma_f32 v34, v156, v156, v34
	v_fma_f32 v7, v168, v168, v7
	v_fma_f32 v8, v164, v164, v8
	v_fma_f32 v42, v162, v162, v42
	v_fma_f32 v34, v158, v158, v34
	v_fma_f32 v7, v170, v170, v7
	v_fma_f32 v8, v166, v166, v8
	v_fma_f32 v42, v163, v163, v42
	v_fma_f32 v34, v159, v159, v34
	v_fma_f32 v7, v171, v171, v7
	v_fma_f32 v8, v167, v167, v8
	v_add_f32_e32 v34, v42, v34
	v_add_f32_e32 v34, v8, v34
	v_add_f32_e32 v34, v7, v34
	s_waitcnt vmcnt(0)
	v_mul_f32_e32 v43, v177, v177
	v_mul_f32_e32 v35, v173, v173
	v_mul_f32_e32 v7, v185, v185
	v_mul_f32_e32 v8, v181, v181
	v_fma_f32 v43, v176, v176, v43
	v_fma_f32 v35, v172, v172, v35
	v_fma_f32 v7, v184, v184, v7
	v_fma_f32 v8, v180, v180, v8
	v_fma_f32 v43, v178, v178, v43
	v_fma_f32 v35, v174, v174, v35
	v_fma_f32 v7, v186, v186, v7
	v_fma_f32 v8, v182, v182, v8
	v_fma_f32 v43, v179, v179, v43
	v_fma_f32 v35, v175, v175, v35
	v_fma_f32 v7, v187, v187, v7
	v_fma_f32 v8, v183, v183, v8
	v_add_f32_e32 v35, v43, v35
	v_add_f32_e32 v35, v8, v35
	v_add_f32_e32 v35, v7, v35
	ds_bpermute_b32 v36, v44, v28
	ds_bpermute_b32 v37, v44, v29
	ds_bpermute_b32 v38, v44, v30
	ds_bpermute_b32 v39, v44, v31
	ds_bpermute_b32 v40, v44, v32
	ds_bpermute_b32 v41, v44, v33
	ds_bpermute_b32 v42, v44, v34
	ds_bpermute_b32 v43, v44, v35
	s_waitcnt lgkmcnt(7)
	v_add_f32_e32 v28, v28, v36
	s_waitcnt lgkmcnt(6)
	v_add_f32_e32 v29, v29, v37
	s_waitcnt lgkmcnt(5)
	v_add_f32_e32 v30, v30, v38
	s_waitcnt lgkmcnt(4)
	v_add_f32_e32 v31, v31, v39
	s_waitcnt lgkmcnt(3)
	v_add_f32_e32 v32, v32, v40
	s_waitcnt lgkmcnt(2)
	v_add_f32_e32 v33, v33, v41
	s_waitcnt lgkmcnt(1)
	v_add_f32_e32 v34, v34, v42
	s_waitcnt lgkmcnt(0)
	v_add_f32_e32 v35, v35, v43
	ds_bpermute_b32 v36, v45, v28
	ds_bpermute_b32 v37, v45, v29
	ds_bpermute_b32 v38, v45, v30
	ds_bpermute_b32 v39, v45, v31
	ds_bpermute_b32 v40, v45, v32
	ds_bpermute_b32 v41, v45, v33
	ds_bpermute_b32 v42, v45, v34
	ds_bpermute_b32 v43, v45, v35
	s_waitcnt lgkmcnt(7)
	v_add_f32_e32 v28, v28, v36
	s_waitcnt lgkmcnt(6)
	v_add_f32_e32 v29, v29, v37
	s_waitcnt lgkmcnt(5)
	v_add_f32_e32 v30, v30, v38
	s_waitcnt lgkmcnt(4)
	v_add_f32_e32 v31, v31, v39
	s_waitcnt lgkmcnt(3)
	v_add_f32_e32 v32, v32, v40
	s_waitcnt lgkmcnt(2)
	v_add_f32_e32 v33, v33, v41
	s_waitcnt lgkmcnt(1)
	v_add_f32_e32 v34, v34, v42
	s_waitcnt lgkmcnt(0)
	v_add_f32_e32 v35, v35, v43
	ds_bpermute_b32 v36, v46, v28
	ds_bpermute_b32 v37, v46, v29
	ds_bpermute_b32 v38, v46, v30
	ds_bpermute_b32 v39, v46, v31
	ds_bpermute_b32 v40, v46, v32
	ds_bpermute_b32 v41, v46, v33
	ds_bpermute_b32 v42, v46, v34
	ds_bpermute_b32 v43, v46, v35
	s_waitcnt lgkmcnt(7)
	v_add_f32_e32 v28, v28, v36
	s_waitcnt lgkmcnt(6)
	v_add_f32_e32 v29, v29, v37
	s_waitcnt lgkmcnt(5)
	v_add_f32_e32 v30, v30, v38
	s_waitcnt lgkmcnt(4)
	v_add_f32_e32 v31, v31, v39
	s_waitcnt lgkmcnt(3)
	v_add_f32_e32 v32, v32, v40
	s_waitcnt lgkmcnt(2)
	v_add_f32_e32 v33, v33, v41
	s_waitcnt lgkmcnt(1)
	v_add_f32_e32 v34, v34, v42
	s_waitcnt lgkmcnt(0)
	v_add_f32_e32 v35, v35, v43
	ds_bpermute_b32 v36, v47, v28
	ds_bpermute_b32 v37, v47, v29
	ds_bpermute_b32 v38, v47, v30
	ds_bpermute_b32 v39, v47, v31
	ds_bpermute_b32 v40, v47, v32
	ds_bpermute_b32 v41, v47, v33
	ds_bpermute_b32 v42, v47, v34
	ds_bpermute_b32 v43, v47, v35
	s_waitcnt lgkmcnt(7)
	v_add_f32_e32 v28, v28, v36
	s_waitcnt lgkmcnt(6)
	v_add_f32_e32 v29, v29, v37
	s_waitcnt lgkmcnt(5)
	v_add_f32_e32 v30, v30, v38
	s_waitcnt lgkmcnt(4)
	v_add_f32_e32 v31, v31, v39
	s_waitcnt lgkmcnt(3)
	v_add_f32_e32 v32, v32, v40
	s_waitcnt lgkmcnt(2)
	v_add_f32_e32 v33, v33, v41
	s_waitcnt lgkmcnt(1)
	v_add_f32_e32 v34, v34, v42
	s_waitcnt lgkmcnt(0)
	v_add_f32_e32 v35, v35, v43
	ds_bpermute_b32 v36, v5, v28
	ds_bpermute_b32 v37, v5, v29
	ds_bpermute_b32 v38, v5, v30
	ds_bpermute_b32 v39, v5, v31
	ds_bpermute_b32 v40, v5, v32
	ds_bpermute_b32 v41, v5, v33
	ds_bpermute_b32 v42, v5, v34
	ds_bpermute_b32 v43, v5, v35
	s_waitcnt lgkmcnt(7)
	v_add_f32_e32 v28, v28, v36
	s_waitcnt lgkmcnt(6)
	v_add_f32_e32 v29, v29, v37
	s_waitcnt lgkmcnt(5)
	v_add_f32_e32 v30, v30, v38
	s_waitcnt lgkmcnt(4)
	v_add_f32_e32 v31, v31, v39
	s_waitcnt lgkmcnt(3)
	v_add_f32_e32 v32, v32, v40
	s_waitcnt lgkmcnt(2)
	v_add_f32_e32 v33, v33, v41
	s_waitcnt lgkmcnt(1)
	v_add_f32_e32 v34, v34, v42
	s_waitcnt lgkmcnt(0)
; __device__ __forceinline__ unsigned pk2(float lo, float hi) { unsigned r; asm("v_cvt_pk_bf16_f32 %0, %1, %2" : "=v"(r) : "v"(lo), "v"(hi)); return r; }
; __device__ __forceinline__ void norm_phase(const float* y, const float* gy, const float* xin, float* xo, const float* gn, bf16_t* h) {
;     ...
;             ss = wave_sum(ss); const float rs = rsqrtf(ss * (1.f / 1024.f) + EPS);
; #pragma unroll
;             for (int i = 0; i < 4; ++i) { const f32x4 gv = *(const f32x4*)(gn + lane * 4 + i * 256); const f32x4 o = xv[i] * rs * gv;
;                 u32x2 w; w.x = pk2(o[0], o[1]); w.y = pk2(o[2], o[3]); *(u32x2*)(h + (size_t)row * D + lane * 4 + i * 256) = w; }
	v_add_f32_e32 v35, v35, v43
	ds_bpermute_b32 v36, v6, v28
	ds_bpermute_b32 v37, v6, v29
	ds_bpermute_b32 v38, v6, v30
	ds_bpermute_b32 v39, v6, v31
	ds_bpermute_b32 v40, v6, v32
	ds_bpermute_b32 v41, v6, v33
	ds_bpermute_b32 v42, v6, v34
	ds_bpermute_b32 v43, v6, v35
	s_waitcnt lgkmcnt(7)
	v_add_f32_e32 v28, v28, v36
	s_waitcnt lgkmcnt(6)
	v_add_f32_e32 v29, v29, v37
	s_waitcnt lgkmcnt(5)
	v_add_f32_e32 v30, v30, v38
	s_waitcnt lgkmcnt(4)
	v_add_f32_e32 v31, v31, v39
	s_waitcnt lgkmcnt(3)
	v_add_f32_e32 v32, v32, v40
	s_waitcnt lgkmcnt(2)
	v_add_f32_e32 v33, v33, v41
	s_waitcnt lgkmcnt(1)
	v_add_f32_e32 v34, v34, v42
	s_waitcnt lgkmcnt(0)
	v_add_f32_e32 v35, v35, v43
	v_fmamk_f32 v28, v28, 0x3a800000, v204
	v_fmamk_f32 v29, v29, 0x3a800000, v204
	v_fmamk_f32 v30, v30, 0x3a800000, v204
	v_fmamk_f32 v31, v31, 0x3a800000, v204
	v_fmamk_f32 v32, v32, 0x3a800000, v204
	v_fmamk_f32 v33, v33, 0x3a800000, v204
	v_fmamk_f32 v34, v34, 0x3a800000, v204
	v_fmamk_f32 v35, v35, 0x3a800000, v204
	v_mul_f32_e32 v36, 0x4b800000, v28
	v_cmp_gt_f32_e32 vcc, s93, v28
	s_nop 1
	v_cndmask_b32_e32 v28, v28, v36, vcc
	v_rsq_f32_e32 v28, v28
	s_nop 0
	v_mul_f32_e32 v36, 0x45800000, v28
	v_cndmask_b32_e32 v214, v28, v36, vcc
	v_mul_f32_e32 v37, 0x4b800000, v29
	v_cmp_gt_f32_e32 vcc, s93, v29
	s_nop 1
	v_cndmask_b32_e32 v29, v29, v37, vcc
	v_rsq_f32_e32 v29, v29
	s_nop 0
	v_mul_f32_e32 v37, 0x45800000, v29
	v_cndmask_b32_e32 v216, v29, v37, vcc
	v_mul_f32_e32 v38, 0x4b800000, v30
	v_cmp_gt_f32_e32 vcc, s93, v30
	s_nop 1
	v_cndmask_b32_e32 v30, v30, v38, vcc
	v_rsq_f32_e32 v30, v30
	s_nop 0
	v_mul_f32_e32 v38, 0x45800000, v30
	v_cndmask_b32_e32 v218, v30, v38, vcc
	v_mul_f32_e32 v39, 0x4b800000, v31
	v_cmp_gt_f32_e32 vcc, s93, v31
	s_nop 1
	v_cndmask_b32_e32 v31, v31, v39, vcc
	v_rsq_f32_e32 v31, v31
	s_nop 0
	v_mul_f32_e32 v39, 0x45800000, v31
	v_cndmask_b32_e32 v220, v31, v39, vcc
	v_mul_f32_e32 v40, 0x4b800000, v32
	v_cmp_gt_f32_e32 vcc, s93, v32
	s_nop 1
	v_cndmask_b32_e32 v32, v32, v40, vcc
	v_rsq_f32_e32 v32, v32
	s_nop 0
	v_mul_f32_e32 v40, 0x45800000, v32
	v_cndmask_b32_e32 v222, v32, v40, vcc
	v_mul_f32_e32 v41, 0x4b800000, v33
	v_cmp_gt_f32_e32 vcc, s93, v33
	s_nop 1
	v_cndmask_b32_e32 v33, v33, v41, vcc
	v_rsq_f32_e32 v33, v33
	s_nop 0
	v_mul_f32_e32 v41, 0x45800000, v33
	v_cndmask_b32_e32 v224, v33, v41, vcc
	v_mul_f32_e32 v42, 0x4b800000, v34
	v_cmp_gt_f32_e32 vcc, s93, v34
	s_nop 1
	v_cndmask_b32_e32 v34, v34, v42, vcc
	v_rsq_f32_e32 v34, v34
	s_nop 0
	v_mul_f32_e32 v42, 0x45800000, v34
	v_cndmask_b32_e32 v226, v34, v42, vcc
	v_mul_f32_e32 v43, 0x4b800000, v35
	v_cmp_gt_f32_e32 vcc, s93, v35
	s_nop 1
	v_cndmask_b32_e32 v35, v35, v43, vcc
	v_rsq_f32_e32 v35, v35
	s_nop 0
	v_mul_f32_e32 v43, 0x45800000, v35
	v_cndmask_b32_e32 v228, v35, v43, vcc
	v_pk_mul_f32 v[48:49], v[48:49], v[214:215] op_sel_hi:[1,0]
	v_pk_mul_f32 v[50:51], v[50:51], v[214:215] op_sel_hi:[1,0]
	v_pk_mul_f32 v[48:49], v[12:13], v[48:49]
	v_pk_mul_f32 v[50:51], v[14:15], v[50:51]
	v_cvt_pk_bf16_f32 v48, v48, v49
	v_cvt_pk_bf16_f32 v49, v50, v51
	global_store_dwordx2 v4, v[48:49], s[10:11] offset:0
	v_pk_mul_f32 v[52:53], v[52:53], v[214:215] op_sel_hi:[1,0]
	v_pk_mul_f32 v[54:55], v[54:55], v[214:215] op_sel_hi:[1,0]
	v_pk_mul_f32 v[52:53], v[16:17], v[52:53]
	v_pk_mul_f32 v[54:55], v[18:19], v[54:55]
	v_cvt_pk_bf16_f32 v52, v52, v53
	v_cvt_pk_bf16_f32 v53, v54, v55
	global_store_dwordx2 v4, v[52:53], s[10:11] offset:512
	v_pk_mul_f32 v[56:57], v[56:57], v[214:215] op_sel_hi:[1,0]
	v_pk_mul_f32 v[58:59], v[58:59], v[214:215] op_sel_hi:[1,0]
	v_pk_mul_f32 v[56:57], v[20:21], v[56:57]
	v_pk_mul_f32 v[58:59], v[22:23], v[58:59]
	v_cvt_pk_bf16_f32 v56, v56, v57
	v_cvt_pk_bf16_f32 v57, v58, v59
	global_store_dwordx2 v4, v[56:57], s[10:11] offset:1024
	v_pk_mul_f32 v[60:61], v[60:61], v[214:215] op_sel_hi:[1,0]
	v_pk_mul_f32 v[62:63], v[62:63], v[214:215] op_sel_hi:[1,0]
	v_pk_mul_f32 v[60:61], v[24:25], v[60:61]
	v_pk_mul_f32 v[62:63], v[26:27], v[62:63]
	v_cvt_pk_bf16_f32 v60, v60, v61
	v_cvt_pk_bf16_f32 v61, v62, v63
	global_store_dwordx2 v4, v[60:61], s[10:11] offset:1536
	s_add_u32 s10, s10, 0x400000
	s_addc_u32 s11, s11, 0
	v_pk_mul_f32 v[64:65], v[64:65], v[216:217] op_sel_hi:[1,0]
	v_pk_mul_f32 v[66:67], v[66:67], v[216:217] op_sel_hi:[1,0]
	v_pk_mul_f32 v[64:65], v[12:13], v[64:65]
	v_pk_mul_f32 v[66:67], v[14:15], v[66:67]
	v_cvt_pk_bf16_f32 v64, v64, v65
	v_cvt_pk_bf16_f32 v65, v66, v67
	global_store_dwordx2 v4, v[64:65], s[10:11] offset:0
	v_pk_mul_f32 v[68:69], v[68:69], v[216:217] op_sel_hi:[1,0]
	v_pk_mul_f32 v[70:71], v[70:71], v[216:217] op_sel_hi:[1,0]
	v_pk_mul_f32 v[68:69], v[16:17], v[68:69]
	v_pk_mul_f32 v[70:71], v[18:19], v[70:71]
	v_cvt_pk_bf16_f32 v68, v68, v69
	v_cvt_pk_bf16_f32 v69, v70, v71
	global_store_dwordx2 v4, v[68:69], s[10:11] offset:512
	v_pk_mul_f32 v[72:73], v[72:73], v[216:217] op_sel_hi:[1,0]
	v_pk_mul_f32 v[74:75], v[74:75], v[216:217] op_sel_hi:[1,0]
	v_pk_mul_f32 v[72:73], v[20:21], v[72:73]
	v_pk_mul_f32 v[74:75], v[22:23], v[74:75]
	v_cvt_pk_bf16_f32 v72, v72, v73
	v_cvt_pk_bf16_f32 v73, v74, v75
	global_store_dwordx2 v4, v[72:73], s[10:11] offset:1024
	v_pk_mul_f32 v[76:77], v[76:77], v[216:217] op_sel_hi:[1,0]
	v_pk_mul_f32 v[78:79], v[78:79], v[216:217] op_sel_hi:[1,0]
	v_pk_mul_f32 v[76:77], v[24:25], v[76:77]
	v_pk_mul_f32 v[78:79], v[26:27], v[78:79]
	v_cvt_pk_bf16_f32 v76, v76, v77
	v_cvt_pk_bf16_f32 v77, v78, v79
	global_store_dwordx2 v4, v[76:77], s[10:11] offset:1536
	s_add_u32 s10, s10, 0x400000
	s_addc_u32 s11, s11, 0
	v_pk_mul_f32 v[80:81], v[80:81], v[218:219] op_sel_hi:[1,0]
	v_pk_mul_f32 v[82:83], v[82:83], v[218:219] op_sel_hi:[1,0]
; __device__ __forceinline__ unsigned pk2(float lo, float hi) { unsigned r; asm("v_cvt_pk_bf16_f32 %0, %1, %2" : "=v"(r) : "v"(lo), "v"(hi)); return r; }
; __device__ __forceinline__ void norm_phase(const float* y, const float* gy, const float* xin, float* xo, const float* gn, bf16_t* h) {
;     ...
; #pragma unroll
;             for (int i = 0; i < 4; ++i) { const f32x4 gv = *(const f32x4*)(gn + lane * 4 + i * 256); const f32x4 o = xv[i] * rs * gv;
;                 u32x2 w; w.x = pk2(o[0], o[1]); w.y = pk2(o[2], o[3]); *(u32x2*)(h + (size_t)row * D + lane * 4 + i * 256) = w; }
	v_pk_mul_f32 v[80:81], v[12:13], v[80:81]
	v_pk_mul_f32 v[82:83], v[14:15], v[82:83]
	v_cvt_pk_bf16_f32 v80, v80, v81
	v_cvt_pk_bf16_f32 v81, v82, v83
	global_store_dwordx2 v4, v[80:81], s[10:11] offset:0
	v_pk_mul_f32 v[84:85], v[84:85], v[218:219] op_sel_hi:[1,0]
	v_pk_mul_f32 v[86:87], v[86:87], v[218:219] op_sel_hi:[1,0]
	v_pk_mul_f32 v[84:85], v[16:17], v[84:85]
	v_pk_mul_f32 v[86:87], v[18:19], v[86:87]
	v_cvt_pk_bf16_f32 v84, v84, v85
	v_cvt_pk_bf16_f32 v85, v86, v87
	global_store_dwordx2 v4, v[84:85], s[10:11] offset:512
	v_pk_mul_f32 v[88:89], v[88:89], v[218:219] op_sel_hi:[1,0]
	v_pk_mul_f32 v[90:91], v[90:91], v[218:219] op_sel_hi:[1,0]
	v_pk_mul_f32 v[88:89], v[20:21], v[88:89]
	v_pk_mul_f32 v[90:91], v[22:23], v[90:91]
	v_cvt_pk_bf16_f32 v88, v88, v89
	v_cvt_pk_bf16_f32 v89, v90, v91
	global_store_dwordx2 v4, v[88:89], s[10:11] offset:1024
	v_pk_mul_f32 v[92:93], v[92:93], v[218:219] op_sel_hi:[1,0]
	v_pk_mul_f32 v[94:95], v[94:95], v[218:219] op_sel_hi:[1,0]
	v_pk_mul_f32 v[92:93], v[24:25], v[92:93]
	v_pk_mul_f32 v[94:95], v[26:27], v[94:95]
	v_cvt_pk_bf16_f32 v92, v92, v93
	v_cvt_pk_bf16_f32 v93, v94, v95
	global_store_dwordx2 v4, v[92:93], s[10:11] offset:1536
	s_add_u32 s10, s10, 0x400000
	s_addc_u32 s11, s11, 0
	v_pk_mul_f32 v[96:97], v[96:97], v[220:221] op_sel_hi:[1,0]
	v_pk_mul_f32 v[98:99], v[98:99], v[220:221] op_sel_hi:[1,0]
	v_pk_mul_f32 v[96:97], v[12:13], v[96:97]
	v_pk_mul_f32 v[98:99], v[14:15], v[98:99]
	v_cvt_pk_bf16_f32 v96, v96, v97
	v_cvt_pk_bf16_f32 v97, v98, v99
	global_store_dwordx2 v4, v[96:97], s[10:11] offset:0
	v_pk_mul_f32 v[100:101], v[100:101], v[220:221] op_sel_hi:[1,0]
	v_pk_mul_f32 v[102:103], v[102:103], v[220:221] op_sel_hi:[1,0]
	v_pk_mul_f32 v[100:101], v[16:17], v[100:101]
	v_pk_mul_f32 v[102:103], v[18:19], v[102:103]
	v_cvt_pk_bf16_f32 v100, v100, v101
	v_cvt_pk_bf16_f32 v101, v102, v103
	global_store_dwordx2 v4, v[100:101], s[10:11] offset:512
	v_pk_mul_f32 v[104:105], v[104:105], v[220:221] op_sel_hi:[1,0]
	v_pk_mul_f32 v[106:107], v[106:107], v[220:221] op_sel_hi:[1,0]
	v_pk_mul_f32 v[104:105], v[20:21], v[104:105]
	v_pk_mul_f32 v[106:107], v[22:23], v[106:107]
	v_cvt_pk_bf16_f32 v104, v104, v105
	v_cvt_pk_bf16_f32 v105, v106, v107
	global_store_dwordx2 v4, v[104:105], s[10:11] offset:1024
	v_pk_mul_f32 v[108:109], v[108:109], v[220:221] op_sel_hi:[1,0]
	v_pk_mul_f32 v[110:111], v[110:111], v[220:221] op_sel_hi:[1,0]
	v_pk_mul_f32 v[108:109], v[24:25], v[108:109]
	v_pk_mul_f32 v[110:111], v[26:27], v[110:111]
	v_cvt_pk_bf16_f32 v108, v108, v109
	v_cvt_pk_bf16_f32 v109, v110, v111
	global_store_dwordx2 v4, v[108:109], s[10:11] offset:1536
	s_add_u32 s10, s10, 0x400000
	s_addc_u32 s11, s11, 0
	v_pk_mul_f32 v[112:113], v[112:113], v[222:223] op_sel_hi:[1,0]
	v_pk_mul_f32 v[114:115], v[114:115], v[222:223] op_sel_hi:[1,0]
	v_pk_mul_f32 v[112:113], v[12:13], v[112:113]
	v_pk_mul_f32 v[114:115], v[14:15], v[114:115]
	v_cvt_pk_bf16_f32 v112, v112, v113
	v_cvt_pk_bf16_f32 v113, v114, v115
	global_store_dwordx2 v4, v[112:113], s[10:11] offset:0
	v_pk_mul_f32 v[116:117], v[116:117], v[222:223] op_sel_hi:[1,0]
	v_pk_mul_f32 v[118:119], v[118:119], v[222:223] op_sel_hi:[1,0]
	v_pk_mul_f32 v[116:117], v[16:17], v[116:117]
	v_pk_mul_f32 v[118:119], v[18:19], v[118:119]
	v_cvt_pk_bf16_f32 v116, v116, v117
	v_cvt_pk_bf16_f32 v117, v118, v119
	global_store_dwordx2 v4, v[116:117], s[10:11] offset:512
	v_pk_mul_f32 v[120:121], v[120:121], v[222:223] op_sel_hi:[1,0]
	v_pk_mul_f32 v[122:123], v[122:123], v[222:223] op_sel_hi:[1,0]
	v_pk_mul_f32 v[120:121], v[20:21], v[120:121]
	v_pk_mul_f32 v[122:123], v[22:23], v[122:123]
	v_cvt_pk_bf16_f32 v120, v120, v121
	v_cvt_pk_bf16_f32 v121, v122, v123
	global_store_dwordx2 v4, v[120:121], s[10:11] offset:1024
	v_pk_mul_f32 v[124:125], v[124:125], v[222:223] op_sel_hi:[1,0]
	v_pk_mul_f32 v[126:127], v[126:127], v[222:223] op_sel_hi:[1,0]
	v_pk_mul_f32 v[124:125], v[24:25], v[124:125]
	v_pk_mul_f32 v[126:127], v[26:27], v[126:127]
	v_cvt_pk_bf16_f32 v124, v124, v125
	v_cvt_pk_bf16_f32 v125, v126, v127
	global_store_dwordx2 v4, v[124:125], s[10:11] offset:1536
	s_add_u32 s10, s10, 0x400000
	s_addc_u32 s11, s11, 0
	v_pk_mul_f32 v[128:129], v[128:129], v[224:225] op_sel_hi:[1,0]
	v_pk_mul_f32 v[130:131], v[130:131], v[224:225] op_sel_hi:[1,0]
	v_pk_mul_f32 v[128:129], v[12:13], v[128:129]
	v_pk_mul_f32 v[130:131], v[14:15], v[130:131]
	v_cvt_pk_bf16_f32 v128, v128, v129
	v_cvt_pk_bf16_f32 v129, v130, v131
	global_store_dwordx2 v4, v[128:129], s[10:11] offset:0
; __device__ __forceinline__ unsigned pk2(float lo, float hi) { unsigned r; asm("v_cvt_pk_bf16_f32 %0, %1, %2" : "=v"(r) : "v"(lo), "v"(hi)); return r; }
; __device__ __forceinline__ int opaque_bid() { int t = blockIdx.x; asm volatile("" : "+s"(t)); return t; }
; __device__ __forceinline__ int opaque_gd() { int t = gridDim.x; asm volatile("" : "+s"(t)); return t; }
; __device__ __forceinline__ void norm_phase(const float* y, const float* gy, const float* xin, float* xo, const float* gn, bf16_t* h) {
;     ...
;     for (int row = opaque_bid() * 8 + wid; row < M; row += opaque_gd() * 8) {
;         f32x4 xv[4]; const float* xr = xin + (size_t)row * D + lane * 4;
;     ...
;             for (int i = 0; i < 4; ++i) { const f32x4 gv = *(const f32x4*)(gn + lane * 4 + i * 256); const f32x4 o = xv[i] * rs * gv;
;                 u32x2 w; w.x = pk2(o[0], o[1]); w.y = pk2(o[2], o[3]); *(u32x2*)(h + (size_t)row * D + lane * 4 + i * 256) = w; }
	v_pk_mul_f32 v[132:133], v[132:133], v[224:225] op_sel_hi:[1,0]
	v_pk_mul_f32 v[134:135], v[134:135], v[224:225] op_sel_hi:[1,0]
	v_pk_mul_f32 v[132:133], v[16:17], v[132:133]
	v_pk_mul_f32 v[134:135], v[18:19], v[134:135]
	v_cvt_pk_bf16_f32 v132, v132, v133
	v_cvt_pk_bf16_f32 v133, v134, v135
	global_store_dwordx2 v4, v[132:133], s[10:11] offset:512
	v_pk_mul_f32 v[148:149], v[148:149], v[224:225] op_sel_hi:[1,0]
	v_pk_mul_f32 v[150:151], v[150:151], v[224:225] op_sel_hi:[1,0]
	v_pk_mul_f32 v[148:149], v[20:21], v[148:149]
	v_pk_mul_f32 v[150:151], v[22:23], v[150:151]
	v_cvt_pk_bf16_f32 v148, v148, v149
	v_cvt_pk_bf16_f32 v149, v150, v151
	global_store_dwordx2 v4, v[148:149], s[10:11] offset:1024
	v_pk_mul_f32 v[152:153], v[152:153], v[224:225] op_sel_hi:[1,0]
	v_pk_mul_f32 v[154:155], v[154:155], v[224:225] op_sel_hi:[1,0]
	v_pk_mul_f32 v[152:153], v[24:25], v[152:153]
	v_pk_mul_f32 v[154:155], v[26:27], v[154:155]
	v_cvt_pk_bf16_f32 v152, v152, v153
	v_cvt_pk_bf16_f32 v153, v154, v155
	global_store_dwordx2 v4, v[152:153], s[10:11] offset:1536
	s_add_u32 s10, s10, 0x400000
	s_addc_u32 s11, s11, 0
	v_pk_mul_f32 v[156:157], v[156:157], v[226:227] op_sel_hi:[1,0]
	v_pk_mul_f32 v[158:159], v[158:159], v[226:227] op_sel_hi:[1,0]
	v_pk_mul_f32 v[156:157], v[12:13], v[156:157]
	v_pk_mul_f32 v[158:159], v[14:15], v[158:159]
	v_cvt_pk_bf16_f32 v156, v156, v157
	v_cvt_pk_bf16_f32 v157, v158, v159
	global_store_dwordx2 v4, v[156:157], s[10:11] offset:0
	v_pk_mul_f32 v[160:161], v[160:161], v[226:227] op_sel_hi:[1,0]
	v_pk_mul_f32 v[162:163], v[162:163], v[226:227] op_sel_hi:[1,0]
	v_pk_mul_f32 v[160:161], v[16:17], v[160:161]
	v_pk_mul_f32 v[162:163], v[18:19], v[162:163]
	v_cvt_pk_bf16_f32 v160, v160, v161
	v_cvt_pk_bf16_f32 v161, v162, v163
	global_store_dwordx2 v4, v[160:161], s[10:11] offset:512
	v_pk_mul_f32 v[164:165], v[164:165], v[226:227] op_sel_hi:[1,0]
	v_pk_mul_f32 v[166:167], v[166:167], v[226:227] op_sel_hi:[1,0]
	v_pk_mul_f32 v[164:165], v[20:21], v[164:165]
	v_pk_mul_f32 v[166:167], v[22:23], v[166:167]
	v_cvt_pk_bf16_f32 v164, v164, v165
	v_cvt_pk_bf16_f32 v165, v166, v167
	global_store_dwordx2 v4, v[164:165], s[10:11] offset:1024
	v_pk_mul_f32 v[168:169], v[168:169], v[226:227] op_sel_hi:[1,0]
	v_pk_mul_f32 v[170:171], v[170:171], v[226:227] op_sel_hi:[1,0]
	v_pk_mul_f32 v[168:169], v[24:25], v[168:169]
	v_pk_mul_f32 v[170:171], v[26:27], v[170:171]
	v_cvt_pk_bf16_f32 v168, v168, v169
	v_cvt_pk_bf16_f32 v169, v170, v171
	global_store_dwordx2 v4, v[168:169], s[10:11] offset:1536
	s_add_u32 s10, s10, 0x400000
	s_addc_u32 s11, s11, 0
	v_pk_mul_f32 v[172:173], v[172:173], v[228:229] op_sel_hi:[1,0]
	v_pk_mul_f32 v[174:175], v[174:175], v[228:229] op_sel_hi:[1,0]
	v_pk_mul_f32 v[172:173], v[12:13], v[172:173]
	v_pk_mul_f32 v[174:175], v[14:15], v[174:175]
	v_cvt_pk_bf16_f32 v172, v172, v173
	v_cvt_pk_bf16_f32 v173, v174, v175
	global_store_dwordx2 v4, v[172:173], s[10:11] offset:0
	v_pk_mul_f32 v[176:177], v[176:177], v[228:229] op_sel_hi:[1,0]
	v_pk_mul_f32 v[178:179], v[178:179], v[228:229] op_sel_hi:[1,0]
	v_pk_mul_f32 v[176:177], v[16:17], v[176:177]
	v_pk_mul_f32 v[178:179], v[18:19], v[178:179]
	v_cvt_pk_bf16_f32 v176, v176, v177
	v_cvt_pk_bf16_f32 v177, v178, v179
	global_store_dwordx2 v4, v[176:177], s[10:11] offset:512
	v_pk_mul_f32 v[180:181], v[180:181], v[228:229] op_sel_hi:[1,0]
	v_pk_mul_f32 v[182:183], v[182:183], v[228:229] op_sel_hi:[1,0]
	v_pk_mul_f32 v[180:181], v[20:21], v[180:181]
	v_pk_mul_f32 v[182:183], v[22:23], v[182:183]
	v_cvt_pk_bf16_f32 v180, v180, v181
	v_cvt_pk_bf16_f32 v181, v182, v183
	global_store_dwordx2 v4, v[180:181], s[10:11] offset:1024
	v_pk_mul_f32 v[184:185], v[184:185], v[228:229] op_sel_hi:[1,0]
	v_pk_mul_f32 v[186:187], v[186:187], v[228:229] op_sel_hi:[1,0]
	v_pk_mul_f32 v[184:185], v[24:25], v[184:185]
	v_pk_mul_f32 v[186:187], v[26:27], v[186:187]
	v_cvt_pk_bf16_f32 v184, v184, v185
	v_cvt_pk_bf16_f32 v185, v186, v187
	global_store_dwordx2 v4, v[184:185], s[10:11] offset:1536
	s_branch .LBB0_8
.Lnorm0_slow:
	v_lshlrev_b32_e32 v1, 2, v1
	v_and_b32_e32 v1, 0xfc, v1
	v_readlane_b32 s0, v255, 16
	s_waitcnt vmcnt(2)
	v_lshlrev_b32_e32 v6, 2, v1
	v_mov_b32_e32 v7, v2
	v_readlane_b32 s1, v255, 17
	s_cmp_lg_u64 s[18:19], 0
	s_waitcnt vmcnt(1)
	v_lshlrev_b32_e32 v8, 1, v1
	v_lshl_add_u64 v[4:5], s[0:1], 0, v[6:7]
	v_readlane_b32 s0, v255, 18
	v_readlane_b32 s1, v255, 19
	v_mov_b32_e32 v9, v2
	s_mov_b64 s[6:7], 0
	s_cselect_b64 s[8:9], -1, 0
	v_lshl_add_u64 v[6:7], s[0:1], 0, v[6:7]
	v_lshl_add_u64 v[8:9], s[18:19], 0, v[8:9]
	s_branch .LBB0_735
